# v_g1 + leading-half ALIGN barrier moved after the residual-load issue in P2/P5/P7 epilogues
# speedup vs baseline: 1.0022x; 1.0022x over previous
.LBB0_662:
	v_lshl_add_u32 v190, s83, 8, v196
	v_ashrrev_i32_e32 v191, 31, v190
	v_lshl_or_b32 v80, s82, 8, v197
	v_lshlrev_b64 v[82:83], 11, v[190:191]
	v_lshl_add_u64 v[82:83], s[64:65], 0, v[82:83]
	v_ashrrev_i32_e32 v81, 31, v80
	v_lshl_add_u64 v[188:189], v[80:81], 1, v[82:83]
	global_load_dwordx4 v[204:207], v[188:189], off
	global_load_dwordx4 v[208:211], v[188:189], off offset:256
	s_mov_b32 s10, 0x8000
	v_add_co_u32_e32 v80, vcc, s10, v188
	s_mov_b32 s11, 0x18000
	s_mov_b32 s40, 0x10000
	v_addc_co_u32_e32 v81, vcc, 0, v189, vcc
	v_add_co_u32_e64 v82, s[10:11], s11, v188
	v_add_co_u32_e32 v84, vcc, s40, v188
	s_mov_b32 s41, 0x40000
	v_addc_co_u32_e64 v83, s[10:11], 0, v189, s[10:11]
	v_addc_co_u32_e32 v85, vcc, 0, v189, vcc
	global_load_dwordx4 v[164:167], v[82:83], off
	global_load_dwordx4 v[160:163], v[82:83], off offset:256
	global_load_dwordx4 v[180:183], v[80:81], off
	global_load_dwordx4 v[176:179], v[80:81], off offset:256
	v_add_co_u32_e32 v80, vcc, s41, v188
	global_load_dwordx4 v[172:175], v[84:85], off
	global_load_dwordx4 v[168:171], v[84:85], off offset:256
	v_addc_co_u32_e32 v81, vcc, 0, v189, vcc
	v_add_co_u32_e32 v82, vcc, s76, v188
	global_load_dwordx4 v[156:159], v[80:81], off
	global_load_dwordx4 v[152:155], v[80:81], off offset:256
	v_addc_co_u32_e32 v83, vcc, 0, v189, vcc
	v_add_co_u32_e32 v80, vcc, s77, v188
	global_load_dwordx4 v[132:135], v[82:83], off
	global_load_dwordx4 v[128:131], v[82:83], off offset:256
	v_addc_co_u32_e32 v81, vcc, 0, v189, vcc
	v_add_co_u32_e32 v82, vcc, s78, v188
	global_load_dwordx4 v[108:111], v[80:81], off
	global_load_dwordx4 v[104:107], v[80:81], off offset:256
	v_addc_co_u32_e32 v83, vcc, 0, v189, vcc
	global_load_dwordx4 v[84:87], v[82:83], off
	s_nop 0
	global_load_dwordx4 v[80:83], v[82:83], off offset:256
	s_and_b64 vcc, exec, s[22:23]
	s_cbranch_vccz .Lepibar_p2
	s_barrier
.Lepibar_p2:
	s_lshl_b32 s10, s82, 2
	v_lshlrev_b64 v[190:191], 6, v[190:191]
	s_ashr_i32 s11, s10, 31
	v_lshl_add_u64 v[190:191], s[16:17], 0, v[190:191]
	v_lshl_add_u64 v[190:191], s[10:11], 2, v[190:191]
	v_lshl_add_u64 v[190:191], v[190:191], 0, s[20:21]
	s_waitcnt vmcnt(15)
	v_lshlrev_b32_e32 v212, 16, v204
	v_and_b32_e32 v213, 0xffff0000, v204
	v_lshlrev_b32_e32 v204, 16, v205
	v_and_b32_e32 v205, 0xffff0000, v205
	v_pk_fma_f32 v[204:205], v[138:139], 0.5, v[204:205] op_sel_hi:[1,0,1]
	v_lshlrev_b32_e32 v214, 16, v206
	v_and_b32_e32 v215, 0xffff0000, v206
	v_pk_fma_f32 v[136:137], v[136:137], 0.5, v[212:213] op_sel_hi:[1,0,1]
	v_lshlrev_b32_e32 v206, 16, v207
	v_cvt_pk_bf16_f32 v138, v136, v137
	v_cvt_pk_bf16_f32 v139, v204, v205
	v_pk_mul_f32 v[204:205], v[204:205], v[204:205]
	v_and_b32_e32 v207, 0xffff0000, v207
	v_pk_fma_f32 v[140:141], v[140:141], 0.5, v[214:215] op_sel_hi:[1,0,1]
	v_pk_fma_f32 v[136:137], v[136:137], v[136:137], v[204:205]
	s_waitcnt vmcnt(14)
	v_lshlrev_b32_e32 v216, 16, v208
	v_and_b32_e32 v217, 0xffff0000, v208
	v_pk_fma_f32 v[142:143], v[142:143], 0.5, v[206:207] op_sel_hi:[1,0,1]
	v_pk_fma_f32 v[136:137], v[140:141], v[140:141], v[136:137]
	v_lshlrev_b32_e32 v208, 16, v209
	v_and_b32_e32 v209, 0xffff0000, v209
	v_pk_fma_f32 v[148:149], v[148:149], 0.5, v[216:217] op_sel_hi:[1,0,1]
	v_pk_fma_f32 v[136:137], v[142:143], v[142:143], v[136:137]
	v_lshlrev_b32_e32 v218, 16, v210
	v_and_b32_e32 v219, 0xffff0000, v210
	v_pk_fma_f32 v[150:151], v[150:151], 0.5, v[208:209] op_sel_hi:[1,0,1]
	v_pk_fma_f32 v[136:137], v[148:149], v[148:149], v[136:137]
	v_lshlrev_b32_e32 v210, 16, v211
	v_and_b32_e32 v211, 0xffff0000, v211
	v_pk_fma_f32 v[144:145], v[144:145], 0.5, v[218:219] op_sel_hi:[1,0,1]
	v_pk_fma_f32 v[136:137], v[150:151], v[150:151], v[136:137]
	v_pk_fma_f32 v[146:147], v[146:147], 0.5, v[210:211] op_sel_hi:[1,0,1]
	v_pk_fma_f32 v[136:137], v[144:145], v[144:145], v[136:137]
	v_and_b32_e32 v204, 64, v203
	v_pk_fma_f32 v[136:137], v[146:147], v[146:147], v[136:137]
	v_add_u32_e32 v204, 64, v204
	v_add_f32_e32 v137, v136, v137
	v_xor_b32_e32 v136, 16, v203
	v_cmp_lt_i32_e32 vcc, v136, v204
	v_cvt_pk_bf16_f32 v140, v140, v141
	v_cvt_pk_bf16_f32 v141, v142, v143
	global_store_dwordx4 v[188:189], v[138:141], off
	s_nop 0
	v_cndmask_b32_e32 v136, v203, v136, vcc
	v_lshlrev_b32_e32 v136, 2, v136
	ds_bpermute_b32 v205, v136, v137
	v_cvt_pk_bf16_f32 v140, v148, v149
	v_cvt_pk_bf16_f32 v141, v150, v151
	v_cvt_pk_bf16_f32 v142, v144, v145
	v_cvt_pk_bf16_f32 v143, v146, v147
	s_waitcnt lgkmcnt(0)
	v_add_f32_e32 v138, v137, v205
	v_xor_b32_e32 v137, 32, v203
	v_cmp_lt_i32_e32 vcc, v137, v204
	global_store_dwordx4 v[188:189], v[140:143], off offset:256
	s_nop 0
	v_cndmask_b32_e32 v137, v203, v137, vcc
	v_lshlrev_b32_e32 v137, 2, v137
	ds_bpermute_b32 v139, v137, v138
	s_and_saveexec_b64 s[10:11], s[6:7]
	s_cbranch_execz .LBB0_664
	s_waitcnt lgkmcnt(0)
	v_add_f32_e32 v138, v138, v139
	global_store_dword v[190:191], v138, off

.LBB0_1132:
	v_lshl_add_u32 v192, s8, 8, v197
	v_ashrrev_i32_e32 v193, 31, v192
	v_lshl_or_b32 v80, s38, 8, v198
	v_lshlrev_b64 v[82:83], 11, v[192:193]
	v_lshl_add_u64 v[82:83], s[64:65], 0, v[82:83]
	v_ashrrev_i32_e32 v81, 31, v80
	v_lshl_add_u64 v[190:191], v[80:81], 1, v[82:83]
	global_load_dwordx4 v[206:209], v[190:191], off
	global_load_dwordx4 v[210:213], v[190:191], off offset:256
	s_mov_b32 s8, 0x8000
	v_add_co_u32_e32 v80, vcc, s8, v190
	s_mov_b32 s9, 0x18000
	s_mov_b32 s29, 0x10000
	v_addc_co_u32_e32 v81, vcc, 0, v191, vcc
	v_add_co_u32_e64 v82, s[8:9], s9, v190
	v_add_co_u32_e32 v84, vcc, s29, v190
	s_mov_b32 s31, 0x40000
	v_addc_co_u32_e64 v83, s[8:9], 0, v191, s[8:9]
	v_addc_co_u32_e32 v85, vcc, 0, v191, vcc
	global_load_dwordx4 v[164:167], v[82:83], off
	global_load_dwordx4 v[160:163], v[82:83], off offset:256
	global_load_dwordx4 v[180:183], v[80:81], off
	global_load_dwordx4 v[176:179], v[80:81], off offset:256
	v_add_co_u32_e32 v80, vcc, s31, v190
	s_mov_b32 s40, 0x48000
	s_nop 0
	v_addc_co_u32_e32 v81, vcc, 0, v191, vcc
	v_add_co_u32_e32 v82, vcc, s40, v190
	global_load_dwordx4 v[172:175], v[84:85], off
	global_load_dwordx4 v[168:171], v[84:85], off offset:256
	v_addc_co_u32_e32 v83, vcc, 0, v191, vcc
	global_load_dwordx4 v[156:159], v[80:81], off
	global_load_dwordx4 v[152:155], v[80:81], off offset:256
	v_add_co_u32_e32 v80, vcc, s80, v190
	global_load_dwordx4 v[132:135], v[82:83], off
	global_load_dwordx4 v[128:131], v[82:83], off offset:256
	v_addc_co_u32_e32 v81, vcc, 0, v191, vcc
	v_add_co_u32_e32 v82, vcc, s81, v190
	global_load_dwordx4 v[108:111], v[80:81], off
	global_load_dwordx4 v[104:107], v[80:81], off offset:256
	v_addc_co_u32_e32 v83, vcc, 0, v191, vcc
	global_load_dwordx4 v[84:87], v[82:83], off
	s_nop 0
	global_load_dwordx4 v[80:83], v[82:83], off offset:256
	s_and_b64 vcc, exec, s[18:19]
	s_cbranch_vccz .Lepibar_p5
	s_barrier
.Lepibar_p5:
	v_and_b32_e32 v205, 64, v204
	v_add_u32_e32 v205, 64, v205
	s_lshl_b32 s8, s38, 2
	v_lshlrev_b64 v[192:193], 6, v[192:193]
	s_ashr_i32 s9, s8, 31
	v_lshl_add_u64 v[192:193], s[10:11], 0, v[192:193]
	v_lshl_add_u64 v[192:193], s[8:9], 2, v[192:193]
	v_lshl_add_u64 v[192:193], v[192:193], 0, s[20:21]
	s_waitcnt vmcnt(15)
	v_lshlrev_b32_e32 v214, 16, v206
	v_and_b32_e32 v215, 0xffff0000, v206
	v_lshlrev_b32_e32 v206, 16, v207
	v_and_b32_e32 v207, 0xffff0000, v207
	v_pk_add_f32 v[206:207], v[138:139], v[206:207]
	v_lshlrev_b32_e32 v216, 16, v208
	v_and_b32_e32 v217, 0xffff0000, v208
	v_pk_add_f32 v[136:137], v[136:137], v[214:215]
	v_lshlrev_b32_e32 v208, 16, v209
	v_cvt_pk_bf16_f32 v138, v136, v137
	v_cvt_pk_bf16_f32 v139, v206, v207
	v_pk_mul_f32 v[206:207], v[206:207], v[206:207]
	v_and_b32_e32 v209, 0xffff0000, v209
	v_pk_add_f32 v[140:141], v[140:141], v[216:217]
	v_pk_fma_f32 v[136:137], v[136:137], v[136:137], v[206:207]
	s_waitcnt vmcnt(14)
	v_lshlrev_b32_e32 v218, 16, v210
	v_and_b32_e32 v219, 0xffff0000, v210
	v_pk_add_f32 v[142:143], v[142:143], v[208:209]
	v_pk_fma_f32 v[136:137], v[140:141], v[140:141], v[136:137]
	v_lshlrev_b32_e32 v210, 16, v211
	v_and_b32_e32 v211, 0xffff0000, v211
	v_pk_add_f32 v[148:149], v[148:149], v[218:219]
	v_pk_fma_f32 v[136:137], v[142:143], v[142:143], v[136:137]
	v_lshlrev_b32_e32 v220, 16, v212
	v_and_b32_e32 v221, 0xffff0000, v212
	v_pk_add_f32 v[150:151], v[150:151], v[210:211]
	v_pk_fma_f32 v[136:137], v[148:149], v[148:149], v[136:137]
	v_lshlrev_b32_e32 v212, 16, v213
	v_and_b32_e32 v213, 0xffff0000, v213
	v_pk_add_f32 v[144:145], v[144:145], v[220:221]
	v_pk_fma_f32 v[136:137], v[150:151], v[150:151], v[136:137]
	v_pk_add_f32 v[146:147], v[146:147], v[212:213]
	v_pk_fma_f32 v[136:137], v[144:145], v[144:145], v[136:137]
	v_cvt_pk_bf16_f32 v140, v140, v141
	v_cvt_pk_bf16_f32 v141, v142, v143
	global_store_dwordx4 v[190:191], v[138:141], off
	v_pk_fma_f32 v[136:137], v[146:147], v[146:147], v[136:137]
	s_nop 0
	v_add_f32_e32 v137, v136, v137
	v_xor_b32_e32 v136, 16, v204
	v_cmp_lt_i32_e32 vcc, v136, v205
	v_cvt_pk_bf16_f32 v140, v148, v149
	v_cvt_pk_bf16_f32 v141, v150, v151
	v_cvt_pk_bf16_f32 v142, v144, v145
	v_cvt_pk_bf16_f32 v143, v146, v147
	global_store_dwordx4 v[190:191], v[140:143], off offset:256
	s_nop 0
	v_cndmask_b32_e32 v136, v204, v136, vcc
	v_lshlrev_b32_e32 v136, 2, v136
	ds_bpermute_b32 v206, v136, v137
	s_waitcnt lgkmcnt(0)
	v_add_f32_e32 v138, v137, v206
	v_xor_b32_e32 v137, 32, v204
	v_cmp_lt_i32_e32 vcc, v137, v205
	s_nop 1
	v_cndmask_b32_e32 v137, v204, v137, vcc
	v_lshlrev_b32_e32 v137, 2, v137
	ds_bpermute_b32 v139, v137, v138
	s_and_saveexec_b64 s[8:9], s[0:1]
	s_cbranch_execz .LBB0_1134
	s_waitcnt lgkmcnt(0)
	v_add_f32_e32 v138, v138, v139
	global_store_dword v[192:193], v138, off

.LBB0_1376:
	v_lshl_add_u32 v112, s53, 8, v172
	v_ashrrev_i32_e32 v113, 31, v112
	v_lshl_or_b32 v114, s54, 8, v173
	v_lshlrev_b64 v[132:133], 11, v[112:113]
	v_lshl_add_u64 v[132:133], s[64:65], 0, v[132:133]
	v_ashrrev_i32_e32 v115, 31, v114
	v_lshl_add_u64 v[132:133], v[114:115], 1, v[132:133]
	v_add_co_u32_e32 v134, vcc, 0x8000, v132
	global_load_dwordx4 v[180:183], v[132:133], off
	global_load_dwordx4 v[184:187], v[132:133], off offset:256
	v_addc_co_u32_e32 v135, vcc, 0, v133, vcc
	global_load_dwordx4 v[188:191], v[134:135], off
	global_load_dwordx4 v[192:195], v[134:135], off offset:256
	v_lshlrev_b64 v[112:113], 12, v[112:113]
	v_lshl_add_u64 v[112:113], s[44:45], 0, v[112:113]
	v_lshl_add_u64 v[166:167], v[114:115], 2, v[112:113]
	v_add_co_u32_e32 v112, vcc, 0x10000, v132
	s_nop 0
	s_nop 0
	v_addc_co_u32_e32 v113, vcc, 0, v133, vcc
	global_load_dwordx4 v[196:199], v[112:113], off
	global_load_dwordx4 v[200:203], v[112:113], off offset:256
	v_add_co_u32_e32 v114, vcc, s26, v132
	s_nop 0
	s_nop 0
	v_addc_co_u32_e32 v115, vcc, 0, v133, vcc
	global_load_dwordx4 v[204:207], v[114:115], off
	global_load_dwordx4 v[160:163], v[114:115], off offset:256
	v_add_co_u32_e32 v112, vcc, 0x40000, v132
	s_nop 0
	s_nop 0
	v_addc_co_u32_e32 v113, vcc, 0, v133, vcc
	global_load_dwordx4 v[156:159], v[112:113], off
	global_load_dwordx4 v[152:155], v[112:113], off offset:256
	v_add_co_u32_e32 v114, vcc, 0x48000, v132
	s_nop 0
	s_nop 0
	v_addc_co_u32_e32 v115, vcc, 0, v133, vcc
	global_load_dwordx4 v[148:151], v[114:115], off
	global_load_dwordx4 v[144:147], v[114:115], off offset:256
	v_add_co_u32_e32 v112, vcc, 0x50000, v132
	s_nop 0
	s_nop 0
	v_addc_co_u32_e32 v113, vcc, 0, v133, vcc
	global_load_dwordx4 v[140:143], v[112:113], off
	global_load_dwordx4 v[136:139], v[112:113], off offset:256
	v_add_co_u32_e32 v114, vcc, 0x58000, v132
	s_nop 0
	s_nop 0
	v_addc_co_u32_e32 v115, vcc, 0, v133, vcc
	global_load_dwordx4 v[132:135], v[114:115], off
	s_nop 0
	global_load_dwordx4 v[112:115], v[114:115], off offset:256
	s_and_b64 vcc, exec, s[6:7]
	s_cbranch_vccz .Lepibar_p7
	s_barrier
.Lepibar_p7:
	s_waitcnt vmcnt(15)
	v_lshlrev_b32_e32 v208, 16, v180
	v_and_b32_e32 v209, 0xffff0000, v180
	v_lshlrev_b32_e32 v180, 16, v181
	v_and_b32_e32 v181, 0xffff0000, v181
	v_lshlrev_b32_e32 v210, 16, v182
	v_and_b32_e32 v211, 0xffff0000, v182
	v_lshlrev_b32_e32 v182, 16, v183
	v_and_b32_e32 v183, 0xffff0000, v183
	s_waitcnt vmcnt(14)
	v_lshlrev_b32_e32 v212, 16, v184
	v_and_b32_e32 v213, 0xffff0000, v184
	v_lshlrev_b32_e32 v184, 16, v185
	v_and_b32_e32 v185, 0xffff0000, v185
	v_lshlrev_b32_e32 v214, 16, v186
	v_and_b32_e32 v215, 0xffff0000, v186
	v_lshlrev_b32_e32 v186, 16, v187
	v_and_b32_e32 v187, 0xffff0000, v187
	v_pk_fma_f32 v[122:123], v[122:123], 0.5, v[180:181] op_sel_hi:[1,0,1]
	v_pk_fma_f32 v[120:121], v[120:121], 0.5, v[208:209] op_sel_hi:[1,0,1]
	v_pk_fma_f32 v[116:117], v[116:117], 0.5, v[210:211] op_sel_hi:[1,0,1]
	v_pk_fma_f32 v[118:119], v[118:119], 0.5, v[182:183] op_sel_hi:[1,0,1]
	v_pk_fma_f32 v[130:131], v[130:131], 0.5, v[184:185] op_sel_hi:[1,0,1]
	v_pk_fma_f32 v[128:129], v[128:129], 0.5, v[212:213] op_sel_hi:[1,0,1]
	v_pk_fma_f32 v[126:127], v[126:127], 0.5, v[186:187] op_sel_hi:[1,0,1]
	v_pk_fma_f32 v[124:125], v[124:125], 0.5, v[214:215] op_sel_hi:[1,0,1]
	global_store_dwordx4 v[166:167], v[120:123], off nt
	global_store_dwordx4 v[166:167], v[116:119], off offset:16 nt
	global_store_dwordx4 v[166:167], v[128:131], off offset:512 nt
	global_store_dwordx4 v[166:167], v[124:127], off offset:528 nt
	s_waitcnt vmcnt(17)
	v_lshlrev_b32_e32 v116, 16, v188
	v_and_b32_e32 v117, 0xffff0000, v188
	v_lshlrev_b32_e32 v118, 16, v189
	v_and_b32_e32 v119, 0xffff0000, v189
	v_lshlrev_b32_e32 v120, 16, v190
	v_and_b32_e32 v121, 0xffff0000, v190
	v_lshlrev_b32_e32 v122, 16, v191
	v_and_b32_e32 v123, 0xffff0000, v191
	v_pk_fma_f32 v[108:109], v[108:109], 0.5, v[116:117] op_sel_hi:[1,0,1]
	v_add_co_u32_e32 v116, vcc, s35, v166
	v_pk_fma_f32 v[110:111], v[110:111], 0.5, v[118:119] op_sel_hi:[1,0,1]
	v_pk_fma_f32 v[106:107], v[106:107], 0.5, v[122:123] op_sel_hi:[1,0,1]
	v_pk_fma_f32 v[104:105], v[104:105], 0.5, v[120:121] op_sel_hi:[1,0,1]
	v_addc_co_u32_e32 v117, vcc, 0, v167, vcc
	global_store_dwordx4 v[116:117], v[108:111], off nt
	global_store_dwordx4 v[116:117], v[104:107], off offset:16 nt
	s_waitcnt vmcnt(18)
	v_lshlrev_b32_e32 v108, 16, v194
	v_lshlrev_b32_e32 v104, 16, v192
	v_and_b32_e32 v105, 0xffff0000, v192
	v_lshlrev_b32_e32 v106, 16, v193
	v_and_b32_e32 v107, 0xffff0000, v193
	v_and_b32_e32 v109, 0xffff0000, v194
	v_lshlrev_b32_e32 v110, 16, v195
	v_and_b32_e32 v111, 0xffff0000, v195
	v_pk_fma_f32 v[102:103], v[102:103], 0.5, v[106:107] op_sel_hi:[1,0,1]
	v_pk_fma_f32 v[100:101], v[100:101], 0.5, v[104:105] op_sel_hi:[1,0,1]
	v_pk_fma_f32 v[96:97], v[96:97], 0.5, v[108:109] op_sel_hi:[1,0,1]
	v_pk_fma_f32 v[98:99], v[98:99], 0.5, v[110:111] op_sel_hi:[1,0,1]
	global_store_dwordx4 v[116:117], v[100:103], off offset:512 nt
	global_store_dwordx4 v[116:117], v[96:99], off offset:528 nt
	s_waitcnt vmcnt(19)
	v_lshlrev_b32_e32 v100, 16, v198
	v_lshlrev_b32_e32 v96, 16, v196
	v_and_b32_e32 v97, 0xffff0000, v196
	v_lshlrev_b32_e32 v98, 16, v197
	v_and_b32_e32 v99, 0xffff0000, v197
	v_and_b32_e32 v101, 0xffff0000, v198
	v_lshlrev_b32_e32 v102, 16, v199
	v_and_b32_e32 v103, 0xffff0000, v199
	v_pk_fma_f32 v[92:93], v[92:93], 0.5, v[96:97] op_sel_hi:[1,0,1]
	v_add_co_u32_e32 v96, vcc, s42, v166
	v_pk_fma_f32 v[94:95], v[94:95], 0.5, v[98:99] op_sel_hi:[1,0,1]
	v_pk_fma_f32 v[90:91], v[90:91], 0.5, v[102:103] op_sel_hi:[1,0,1]
	v_pk_fma_f32 v[88:89], v[88:89], 0.5, v[100:101] op_sel_hi:[1,0,1]
	v_addc_co_u32_e32 v97, vcc, 0, v167, vcc
	global_store_dwordx4 v[96:97], v[92:95], off nt
	global_store_dwordx4 v[96:97], v[88:91], off offset:16 nt
	s_waitcnt vmcnt(20)
	v_lshlrev_b32_e32 v92, 16, v202
	v_lshlrev_b32_e32 v88, 16, v200
	v_and_b32_e32 v89, 0xffff0000, v200
	v_lshlrev_b32_e32 v90, 16, v201
	v_and_b32_e32 v91, 0xffff0000, v201
	v_and_b32_e32 v93, 0xffff0000, v202
	v_lshlrev_b32_e32 v94, 16, v203
	v_and_b32_e32 v95, 0xffff0000, v203
	v_pk_fma_f32 v[86:87], v[86:87], 0.5, v[90:91] op_sel_hi:[1,0,1]
	v_pk_fma_f32 v[84:85], v[84:85], 0.5, v[88:89] op_sel_hi:[1,0,1]
	v_pk_fma_f32 v[80:81], v[80:81], 0.5, v[92:93] op_sel_hi:[1,0,1]
	v_pk_fma_f32 v[82:83], v[82:83], 0.5, v[94:95] op_sel_hi:[1,0,1]
	global_store_dwordx4 v[96:97], v[84:87], off offset:512 nt
	global_store_dwordx4 v[96:97], v[80:83], off offset:528 nt
	s_waitcnt vmcnt(21)
	v_lshlrev_b32_e32 v84, 16, v206
	v_lshlrev_b32_e32 v80, 16, v204
	v_and_b32_e32 v81, 0xffff0000, v204
	v_lshlrev_b32_e32 v82, 16, v205
	v_and_b32_e32 v83, 0xffff0000, v205
	v_and_b32_e32 v85, 0xffff0000, v206
	v_lshlrev_b32_e32 v86, 16, v207
	v_and_b32_e32 v87, 0xffff0000, v207
	v_pk_fma_f32 v[76:77], v[76:77], 0.5, v[80:81] op_sel_hi:[1,0,1]
	v_add_co_u32_e32 v80, vcc, s43, v166
	v_pk_fma_f32 v[78:79], v[78:79], 0.5, v[82:83] op_sel_hi:[1,0,1]
	v_pk_fma_f32 v[74:75], v[74:75], 0.5, v[86:87] op_sel_hi:[1,0,1]
	v_pk_fma_f32 v[72:73], v[72:73], 0.5, v[84:85] op_sel_hi:[1,0,1]
	v_addc_co_u32_e32 v81, vcc, 0, v167, vcc
	global_store_dwordx4 v[80:81], v[76:79], off nt
	global_store_dwordx4 v[80:81], v[72:75], off offset:16 nt
	s_waitcnt vmcnt(22)
	v_lshlrev_b32_e32 v76, 16, v162
	v_lshlrev_b32_e32 v72, 16, v160
	v_and_b32_e32 v73, 0xffff0000, v160
	v_lshlrev_b32_e32 v74, 16, v161
	v_and_b32_e32 v75, 0xffff0000, v161
	v_and_b32_e32 v77, 0xffff0000, v162
	v_lshlrev_b32_e32 v78, 16, v163
	v_and_b32_e32 v79, 0xffff0000, v163
	v_pk_fma_f32 v[62:63], v[62:63], 0.5, v[74:75] op_sel_hi:[1,0,1]
	v_pk_fma_f32 v[60:61], v[60:61], 0.5, v[72:73] op_sel_hi:[1,0,1]
	v_pk_fma_f32 v[58:59], v[58:59], 0.5, v[78:79] op_sel_hi:[1,0,1]
	v_pk_fma_f32 v[56:57], v[56:57], 0.5, v[76:77] op_sel_hi:[1,0,1]
	global_store_dwordx4 v[80:81], v[60:63], off offset:512 nt
	global_store_dwordx4 v[80:81], v[56:59], off offset:528 nt
	s_waitcnt vmcnt(23)
	v_lshlrev_b32_e32 v60, 16, v158
	v_and_b32_e32 v61, 0xffff0000, v158
	v_lshlrev_b32_e32 v56, 16, v156
	v_and_b32_e32 v57, 0xffff0000, v156
	v_lshlrev_b32_e32 v58, 16, v157
	v_and_b32_e32 v59, 0xffff0000, v157
	v_pk_fma_f32 v[60:61], v[64:65], 0.5, v[60:61] op_sel_hi:[1,0,1]
	v_add_co_u32_e32 v64, vcc, s46, v166
	v_lshlrev_b32_e32 v62, 16, v159
	v_and_b32_e32 v63, 0xffff0000, v159
	v_pk_fma_f32 v[58:59], v[70:71], 0.5, v[58:59] op_sel_hi:[1,0,1]
	v_pk_fma_f32 v[56:57], v[68:69], 0.5, v[56:57] op_sel_hi:[1,0,1]
	v_addc_co_u32_e32 v65, vcc, 0, v167, vcc
	v_pk_fma_f32 v[62:63], v[66:67], 0.5, v[62:63] op_sel_hi:[1,0,1]
	global_store_dwordx4 v[64:65], v[56:59], off nt
	global_store_dwordx4 v[64:65], v[60:63], off offset:16 nt
	s_waitcnt vmcnt(24)
	v_lshlrev_b32_e32 v56, 16, v152
	v_and_b32_e32 v57, 0xffff0000, v152
	v_lshlrev_b32_e32 v58, 16, v153
	v_and_b32_e32 v59, 0xffff0000, v153
	v_lshlrev_b32_e32 v60, 16, v154
	v_and_b32_e32 v61, 0xffff0000, v154
	v_lshlrev_b32_e32 v62, 16, v155
	v_and_b32_e32 v63, 0xffff0000, v155
	v_pk_fma_f32 v[54:55], v[54:55], 0.5, v[58:59] op_sel_hi:[1,0,1]
	v_pk_fma_f32 v[52:53], v[52:53], 0.5, v[56:57] op_sel_hi:[1,0,1]
	v_pk_fma_f32 v[48:49], v[48:49], 0.5, v[60:61] op_sel_hi:[1,0,1]
	v_pk_fma_f32 v[50:51], v[50:51], 0.5, v[62:63] op_sel_hi:[1,0,1]
	global_store_dwordx4 v[64:65], v[52:55], off offset:512 nt
	global_store_dwordx4 v[64:65], v[48:51], off offset:528 nt
	s_waitcnt vmcnt(25)
	v_lshlrev_b32_e32 v52, 16, v150
	v_lshlrev_b32_e32 v48, 16, v148
	v_and_b32_e32 v49, 0xffff0000, v148
	v_lshlrev_b32_e32 v50, 16, v149
	v_and_b32_e32 v51, 0xffff0000, v149
	v_and_b32_e32 v53, 0xffff0000, v150
	v_lshlrev_b32_e32 v54, 16, v151
	v_and_b32_e32 v55, 0xffff0000, v151
	v_pk_fma_f32 v[44:45], v[44:45], 0.5, v[48:49] op_sel_hi:[1,0,1]
	v_add_co_u32_e32 v48, vcc, s47, v166
	v_pk_fma_f32 v[46:47], v[46:47], 0.5, v[50:51] op_sel_hi:[1,0,1]
	v_pk_fma_f32 v[42:43], v[42:43], 0.5, v[54:55] op_sel_hi:[1,0,1]
	v_pk_fma_f32 v[40:41], v[40:41], 0.5, v[52:53] op_sel_hi:[1,0,1]
	v_addc_co_u32_e32 v49, vcc, 0, v167, vcc
	global_store_dwordx4 v[48:49], v[44:47], off nt
	global_store_dwordx4 v[48:49], v[40:43], off offset:16 nt
	s_waitcnt vmcnt(26)
	v_lshlrev_b32_e32 v44, 16, v146
	v_lshlrev_b32_e32 v40, 16, v144
	v_and_b32_e32 v41, 0xffff0000, v144
	v_lshlrev_b32_e32 v42, 16, v145
	v_and_b32_e32 v43, 0xffff0000, v145
	v_and_b32_e32 v45, 0xffff0000, v146
	v_lshlrev_b32_e32 v46, 16, v147
	v_and_b32_e32 v47, 0xffff0000, v147
	v_pk_fma_f32 v[38:39], v[38:39], 0.5, v[42:43] op_sel_hi:[1,0,1]
	v_pk_fma_f32 v[36:37], v[36:37], 0.5, v[40:41] op_sel_hi:[1,0,1]
	v_pk_fma_f32 v[32:33], v[32:33], 0.5, v[44:45] op_sel_hi:[1,0,1]
	v_pk_fma_f32 v[34:35], v[34:35], 0.5, v[46:47] op_sel_hi:[1,0,1]
	global_store_dwordx4 v[48:49], v[36:39], off offset:512 nt
	global_store_dwordx4 v[48:49], v[32:35], off offset:528 nt
	s_waitcnt vmcnt(27)
	v_lshlrev_b32_e32 v36, 16, v142
	v_lshlrev_b32_e32 v32, 16, v140
	v_and_b32_e32 v33, 0xffff0000, v140
	v_lshlrev_b32_e32 v34, 16, v141
	v_and_b32_e32 v35, 0xffff0000, v141
	v_and_b32_e32 v37, 0xffff0000, v142
	v_lshlrev_b32_e32 v38, 16, v143
	v_and_b32_e32 v39, 0xffff0000, v143
	v_pk_fma_f32 v[28:29], v[28:29], 0.5, v[32:33] op_sel_hi:[1,0,1]
	v_add_co_u32_e32 v32, vcc, s48, v166
	v_pk_fma_f32 v[30:31], v[30:31], 0.5, v[34:35] op_sel_hi:[1,0,1]
	v_pk_fma_f32 v[26:27], v[26:27], 0.5, v[38:39] op_sel_hi:[1,0,1]
	v_pk_fma_f32 v[24:25], v[24:25], 0.5, v[36:37] op_sel_hi:[1,0,1]
	v_addc_co_u32_e32 v33, vcc, 0, v167, vcc
	global_store_dwordx4 v[32:33], v[28:31], off nt
	global_store_dwordx4 v[32:33], v[24:27], off offset:16 nt
	s_waitcnt vmcnt(28)
	v_lshlrev_b32_e32 v28, 16, v138
	v_lshlrev_b32_e32 v24, 16, v136
	v_and_b32_e32 v25, 0xffff0000, v136
	v_lshlrev_b32_e32 v26, 16, v137
	v_and_b32_e32 v27, 0xffff0000, v137
	v_and_b32_e32 v29, 0xffff0000, v138
	v_lshlrev_b32_e32 v30, 16, v139
	v_and_b32_e32 v31, 0xffff0000, v139
	v_pk_fma_f32 v[22:23], v[22:23], 0.5, v[26:27] op_sel_hi:[1,0,1]
	v_pk_fma_f32 v[20:21], v[20:21], 0.5, v[24:25] op_sel_hi:[1,0,1]
	v_pk_fma_f32 v[16:17], v[16:17], 0.5, v[28:29] op_sel_hi:[1,0,1]
	v_pk_fma_f32 v[18:19], v[18:19], 0.5, v[30:31] op_sel_hi:[1,0,1]
	global_store_dwordx4 v[32:33], v[20:23], off offset:512 nt
	global_store_dwordx4 v[32:33], v[16:19], off offset:528 nt
	s_waitcnt vmcnt(29)
	v_lshlrev_b32_e32 v20, 16, v134
	v_lshlrev_b32_e32 v16, 16, v132
	v_and_b32_e32 v17, 0xffff0000, v132
	v_lshlrev_b32_e32 v18, 16, v133
	v_and_b32_e32 v19, 0xffff0000, v133
	v_and_b32_e32 v21, 0xffff0000, v134
	v_lshlrev_b32_e32 v22, 16, v135
	v_and_b32_e32 v23, 0xffff0000, v135
	v_pk_fma_f32 v[12:13], v[12:13], 0.5, v[16:17] op_sel_hi:[1,0,1]
	v_add_co_u32_e32 v16, vcc, s49, v166
	v_pk_fma_f32 v[14:15], v[14:15], 0.5, v[18:19] op_sel_hi:[1,0,1]
	v_pk_fma_f32 v[10:11], v[10:11], 0.5, v[22:23] op_sel_hi:[1,0,1]
	v_pk_fma_f32 v[8:9], v[8:9], 0.5, v[20:21] op_sel_hi:[1,0,1]
	v_addc_co_u32_e32 v17, vcc, 0, v167, vcc
	global_store_dwordx4 v[16:17], v[12:15], off nt
	global_store_dwordx4 v[16:17], v[8:11], off offset:16 nt
	s_and_b64 vcc, exec, s[0:1]
	s_waitcnt vmcnt(30)
	v_lshlrev_b32_e32 v12, 16, v114
	v_lshlrev_b32_e32 v8, 16, v112
	v_and_b32_e32 v9, 0xffff0000, v112
	v_lshlrev_b32_e32 v10, 16, v113
	v_and_b32_e32 v11, 0xffff0000, v113
	v_and_b32_e32 v13, 0xffff0000, v114
	v_lshlrev_b32_e32 v14, 16, v115
	v_and_b32_e32 v15, 0xffff0000, v115
	v_pk_fma_f32 v[6:7], v[6:7], 0.5, v[10:11] op_sel_hi:[1,0,1]
	v_pk_fma_f32 v[4:5], v[4:5], 0.5, v[8:9] op_sel_hi:[1,0,1]
	s_mov_b64 s[0:1], -1
	v_pk_fma_f32 v[2:3], v[2:3], 0.5, v[14:15] op_sel_hi:[1,0,1]
	v_pk_fma_f32 v[0:1], v[0:1], 0.5, v[12:13] op_sel_hi:[1,0,1]
	global_store_dwordx4 v[16:17], v[4:7], off offset:512 nt
	global_store_dwordx4 v[16:17], v[0:3], off offset:528 nt
	s_cbranch_vccnz .LBB0_1360
	s_andn2_b64 vcc, exec, s[4:5]
	s_cbranch_vccnz .LBB0_1359
	s_barrier
	s_branch .LBB0_1359
